# NSA select/window attention: master bias tables built once per phase, per-item table filled by an LDS-to-LDS copy (no dependent global loads per item); all other code at unchanged addresses
# speedup vs baseline: 1.0002x; 1.0002x over previous
; template <int MODE>
; __device__ __forceinline__ void attn_pass(LAS unsigned char* lds, const bf16_t* base, int gk, int q0, const float* relb_b, const unsigned* selrow, f32x4 (&o)[2][4]) {
;     ...
;         for (int ks = 0; ks < 2; ++ks) qf[qt][ks] = *(const bf16x8*)(qp + (size_t)(qw0 + qt * 16 + c) * QP + ks * 32 + g * 8);
;     const int kb_hi = q0 >> 6;
;     unsigned todo;
;     unsigned sel[2] = {0xffffffffu, 0xffffffffu};
;     unsigned selw = 0xffffffffu;
;     if (MODE == MODE_BSLC) {
;         sel[0] = selrow[qw0 + c]; sel[1] = selrow[qw0 + 16 + c];
;         unsigned u = sel[0] | sel[1];
; #pragma unroll
;         for (int off = 1; off < 64; off <<= 1) u |= __shfl_xor(u, off);
;         selw = __builtin_amdgcn_readfirstlane(u);
;         unsigned v = selrow[q0 + lane];
; #pragma unroll
;         for (int off = 1; off < 64; off <<= 1) v |= __shfl_xor(v, off);
;         todo = __builtin_amdgcn_readfirstlane(v) & (0xffffffffu >> (31 - kb_hi));
;     } else {
;         const int kb_lo = kb_hi >= 8 ? kb_hi - 8 : 0;
;         todo = (0xffffffffu >> (31 - kb_hi)) & (0xffffffffu << kb_lo);
;     }
;     __syncthreads();
;     if (tid < 512) { const int e = tid; lutw[e] = relb_b[(int)T5B[e & 127] * 16 + gk * 4 + (e >> 7)] * LOG2E; }
;     const float bias_far = relb_b[31 * 16 + h] * LOG2E;
.LBB0_53:
	s_or_b64 exec, exec, s[0:1]
	v_readlane_b32 s0, v254, 48
	s_waitcnt lgkmcnt(0)
	s_barrier
	v_mov_b32_e32 v1, s0
	ds_read_b32 v1, v1
	s_movk_i32 s0, 0x7ff
	s_waitcnt lgkmcnt(0)
	v_cmp_lt_i32_e32 vcc, s0, v1
	v_readfirstlane_b32 s5, v1
	s_mov_b64 s[0:1], -1
	s_cbranch_vccnz .LBB0_48
	s_and_b32 s0, s5, 0xffffffc0
	s_bfe_u32 s19, s5, 0x50001
	s_and_b32 s4, s5, 1
	s_sub_i32 s36, 0x7c0, s0
	s_mul_i32 s0, s19, 0xe18000
	v_readlane_b32 s6, v252, 52
	v_readlane_b32 s7, v252, 53
	s_add_u32 s13, s6, s0
	s_addc_u32 s41, s7, 0
	s_lshl_b32 s40, s4, 2
	s_lshl_b32 s0, s19, 14
	v_readlane_b32 s1, v252, 14
	s_add_u32 s0, s1, s0
	v_readlane_b32 s1, v252, 15
	v_mov_b32_e32 v180, v214
	s_addc_u32 s1, s1, 0
	s_lshl_b32 s5, s4, 13
	v_mov_b32_e32 v10, v214
	s_add_u32 s0, s0, s5
	s_addc_u32 s1, s1, 0
	v_readfirstlane_b32 s5, v10
	s_bfe_u32 s7, s5, 0x20006
	s_or_b32 s8, s7, s40
	s_lshl_b32 s6, s8, 7
	s_add_u32 s10, s13, s6
	s_addc_u32 s11, s41, 0
	s_ashr_i32 s5, s5, 3
	s_and_b32 s6, s5, 0xffffffe0
	v_and_b32_e32 v1, 15, v10
	s_add_i32 s6, s6, s36
	v_or_b32_e32 v2, s6, v1
	v_ashrrev_i32_e32 v3, 31, v2
	v_lshl_add_u64 v[8:9], v[2:3], 2, s[0:1]
	v_and_or_b32 v12, v10, 63, s36
	v_mov_b32_e32 v13, v0
	v_lshl_add_u64 v[12:13], v[12:13], 2, s[0:1]
	global_load_dword v146, v[8:9], off
	global_load_dword v147, v[8:9], off offset:64
	global_load_dword v3, v[12:13], off
	v_mov_b32_e32 v9, v0
	v_and_b32_e32 v8, 48, v10
	v_lshl_add_u64 v[12:13], s[10:11], 0, v[8:9]
	v_or_b32_e32 v9, 16, v2
	v_mad_i64_i32 v[14:15], s[0:1], v2, s85, v[12:13]
	v_mad_i64_i32 v[12:13], s[0:1], v9, s85, v[12:13]
	global_load_dwordx4 v[40:43], v[14:15], off offset:1536
	global_load_dwordx4 v[44:47], v[14:15], off offset:1600
	global_load_dwordx4 v[48:51], v[12:13], off offset:1536
	global_load_dwordx4 v[52:55], v[12:13], off offset:1600
	v_cmp_lt_i32_e32 vcc, v219, v218
	s_barrier
	s_nop 0
	v_cndmask_b32_e32 v9, v217, v219, vcc
	v_lshlrev_b32_e32 v9, 2, v9
	v_cmp_lt_i32_e32 vcc, v220, v218
	s_waitcnt vmcnt(5)
	v_or_b32_e32 v11, v147, v146
	s_waitcnt vmcnt(4)
	ds_bpermute_b32 v12, v9, v3
	ds_bpermute_b32 v9, v9, v11
	v_cndmask_b32_e32 v13, v217, v220, vcc
	v_lshlrev_b32_e32 v13, 2, v13
	v_cmp_lt_i32_e32 vcc, v221, v218
	s_waitcnt lgkmcnt(1)
	v_or_b32_e32 v3, v12, v3
	s_waitcnt lgkmcnt(0)
	v_or_b32_e32 v9, v9, v11
	ds_bpermute_b32 v11, v13, v3
	ds_bpermute_b32 v12, v13, v9
	v_cndmask_b32_e32 v13, v217, v221, vcc
	v_lshlrev_b32_e32 v13, 2, v13
	v_cmp_lt_i32_e32 vcc, v222, v218
	s_waitcnt lgkmcnt(1)
	v_or_b32_e32 v3, v11, v3
	s_waitcnt lgkmcnt(0)
	v_or_b32_e32 v9, v12, v9
	ds_bpermute_b32 v11, v13, v3
	ds_bpermute_b32 v12, v13, v9
	v_cndmask_b32_e32 v13, v217, v222, vcc
	v_lshlrev_b32_e32 v13, 2, v13
	v_cmp_lt_i32_e32 vcc, v223, v218
	s_waitcnt lgkmcnt(1)
	v_or_b32_e32 v3, v11, v3
	s_waitcnt lgkmcnt(0)
	v_or_b32_e32 v9, v12, v9
	ds_bpermute_b32 v11, v13, v3
	ds_bpermute_b32 v12, v13, v9
	v_cndmask_b32_e32 v13, v217, v223, vcc
	v_lshlrev_b32_e32 v178, 2, v13
	v_cmp_lt_i32_e32 vcc, v224, v218
	s_waitcnt lgkmcnt(1)
	v_or_b32_e32 v3, v11, v3
	s_waitcnt lgkmcnt(0)
	v_or_b32_e32 v9, v12, v9
	ds_bpermute_b32 v11, v178, v3
	ds_bpermute_b32 v12, v178, v9
	v_cndmask_b32_e32 v13, v217, v224, vcc
	v_lshlrev_b32_e32 v179, 2, v13
	v_cmp_gt_i32_e32 vcc, s33, v10
	s_waitcnt lgkmcnt(1)
	v_or_b32_e32 v3, v11, v3
	s_waitcnt lgkmcnt(0)
	v_or_b32_e32 v9, v12, v9
	ds_bpermute_b32 v11, v179, v3
	ds_bpermute_b32 v12, v179, v9
	s_waitcnt lgkmcnt(1)
	v_or_b32_e32 v3, v11, v3
	s_waitcnt lgkmcnt(0)
	v_or_b32_e32 v9, v12, v9
	v_readfirstlane_b32 s9, v3
	v_readfirstlane_b32 s44, v9
	s_and_saveexec_b64 s[0:1], vcc
	s_cbranch_execz .LBB0_56
	v_lshlrev_b32_e32 v228, 2, v10
	s_mul_i32 s10, s40, 0xa00
	s_add_i32 s10, s10, 0xf000
	v_add_u32_e32 v229, s10, v228
	ds_read_b32 v230, v229
	ds_read_b32 v231, v229 offset:2048
	ds_read_b32 v232, v229 offset:4096
	ds_read_b32 v233, v229 offset:6144
	ds_read_b32 v234, v229 offset:8192
	s_waitcnt lgkmcnt(0)
	ds_write_b32 v228, v230 offset:40960
	ds_write_b32 v228, v231 offset:43008
	ds_write_b32 v228, v232 offset:45056
	ds_write_b32 v228, v233 offset:47104
	ds_write_b32 v228, v234 offset:49152
	s_branch .LBB0_56
.Lattb_tab:
	v_and_b32_e32 v236, 0x7f, v214
	s_getpc_b64 s[10:11]
	s_add_u32 s10, s10, T5B@rel32@lo+4
	s_addc_u32 s11, s11, T5B@rel32@hi+12
	global_load_ubyte v237, v236, s[10:11]
	v_readlane_b32 s52, v255, 8
	v_readlane_b32 s53, v255, 9
	v_ashrrev_i32_e32 v238, 7, v214
	v_mul_u32_u24_e32 v231, 0xa00, v238
	v_lshl_add_u32 v233, v236, 2, v231
	v_add_u32_e32 v233, 0x5000, v233
	v_and_b32_e32 v234, 64, v214
	v_lshl_add_u32 v234, v234, 5, v233
	v_mov_b32_e32 v235, 0xf149f2ca
	v_add_u32_e32 v248, 0x1f0, v238
	v_lshlrev_b32_e32 v248, 2, v248
	s_mov_b32 s10, 0x3fb8aa3b
	s_waitcnt vmcnt(0)
	v_lshl_add_u32 v246, v237, 4, v238
	v_lshlrev_b32_e32 v246, 2, v246
	global_load_dword v241, v246, s[52:53] offset:32
	global_load_dword v243, v246, s[52:53] offset:48
	global_load_dword v242, v248, s[52:53] offset:32
	global_load_dword v244, v248, s[52:53] offset:48
	s_waitcnt vmcnt(0)
	v_mul_f32_e32 v241, s10, v241
	v_mul_f32_e32 v242, s10, v242
	v_mul_f32_e32 v243, s10, v243
	v_mul_f32_e32 v244, s10, v244
	ds_write2st64_b32 v233, v241, v242 offset0:161 offset1:167
	ds_write2st64_b32 v233, v242, v242 offset0:163 offset1:165
	ds_write_b32 v234, v235 offset:40960
	ds_write2st64_b32 v233, v243, v244 offset0:201 offset1:207
	ds_write2st64_b32 v233, v244, v244 offset0:203 offset1:205
	ds_write_b32 v234, v235 offset:51200
	s_waitcnt lgkmcnt(0)
	s_branch .LBB0_49
	s_nop 0
	s_nop 0
